# attention: mask-free copy of the per-tile compute block for non-diagonal key tiles (wave-uniform dispatch)
# speedup vs baseline: 1.0149x; 1.0149x over previous
; #define LAS __attribute__((address_space(3)))
; __device__ __forceinline__ void attn_phase(LAS unsigned char* lds, const int wid, const bf16_t* P, const float* LF, bf16_t* CAT, const float* qgain, const float* kgain) {
;     ...
;                 if (kt * 64 <= q0 + 31 && !done_w) {
;                     const LAS unsigned char* kb_ = KB + cb * 64 * KPITCH;
;                     const LAS unsigned char* vb_ = VB + cb * 64 * VPITCH;
;                     f32x16 sacc[2];
; #pragma unroll
;                     for (int kb = 0; kb < 2; ++kb) {
; #pragma unroll
;                         for (int i = 0; i < 16; ++i) sacc[kb][i] = 0.f;
; #pragma unroll
;                         for (int ds = 0; ds < 4; ++ds) {
;                             const bf16x8 a = *(const LAS bf16x8*)(kb_ + (kb * 32 + r32) * KPITCH + (16 * ds + 8 * hh) * 2);
;                             sacc[kb] = __builtin_amdgcn_mfma_f32_32x32x16_bf16(a, qf[ds], sacc[kb], 0, 0, 0);
;                         }
;                     }
;                     const bool diag = (kt * 64 + 63 > q0);
;                     float mloc = -1e30f;
; #pragma unroll
;                     for (int kb = 0; kb < 2; ++kb)
; #pragma unroll
;                         for (int i4 = 0; i4 < 4; ++i4) {
;                             const int kl = kb * 32 + 8 * i4 + 4 * hh;
;                             const f32x4 bias = *(const LAS f32x4*)(CB + kt * 64 + kl);
; #pragma unroll
;                             for (int jj = 0; jj < 4; ++jj) {
;                                 float sv = sacc[kb][4 * i4 + jj] + bias[jj];
;                                 if (diag && (kt * 64 + kl + jj > qrow)) sv = -1e30f;
;                                 sacc[kb][4 * i4 + jj] = sv; mloc = fmaxf(mloc, sv);
;                             }
;                         }
.LBB0_268:
	s_and_b32 s80, s20, 1
	s_cmp_le_i32 s77, s76
	s_cselect_b64 s[18:19], -1, 0
	v_cmp_eq_u32_e32 vcc, 0, v165
	s_and_b64 s[56:57], s[18:19], vcc
	s_and_saveexec_b64 s[58:59], s[56:57]
	s_cbranch_execz .LBB0_270
	s_add_i32 s19, s77, 63
	s_cmp_gt_i32 s19, s74
	s_cbranch_scc0 .Lattn_nodiag_a
	s_mul_i32 s18, s80, 0x2400
	v_add3_u32 v1, v160, s18, v162
	ds_read_b128 v[2:5], v1 offset:16384
	ds_read_b128 v[6:9], v1 offset:16416
	v_add_u32_e32 v14, s78, v159
	s_add_i32 s18, s77, 63
	v_add_u32_e32 v15, s77, v112
	s_waitcnt lgkmcnt(1)
	v_mfma_f32_32x32x16_bf16 v[64:79], v[2:5], v[88:91], 0
	ds_read_b128 v[2:5], v1 offset:16448
	s_cmp_gt_i32 s18, s74
	v_cmp_gt_i32_e32 vcc, v15, v134
	s_cselect_b64 s[60:61], -1, 0
	v_cmp_ge_i32_e64 s[18:19], v15, v134
	s_and_b64 vcc, s[60:61], vcc
	s_waitcnt lgkmcnt(1)
	v_mfma_f32_32x32x16_bf16 v[64:79], v[6:9], v[92:95], v[64:79]
	ds_read_b128 v[6:9], v1 offset:16480
	ds_read_b128 v[10:13], v1 offset:20992
	s_waitcnt lgkmcnt(2)
	v_mfma_f32_32x32x16_bf16 v[64:79], v[2:5], v[96:99], v[64:79]
	ds_read_b128 v[2:5], v14 offset:4
	ds_read_b128 v[168:171], v14 offset:36
	ds_read_b128 v[172:175], v1 offset:21024
	ds_read_b128 v[176:179], v1 offset:21056
	ds_read_b128 v[180:183], v1 offset:21088
	v_add_u32_e32 v1, 2, v15
	v_cmp_gt_i32_e64 s[20:21], v1, v134
	s_waitcnt lgkmcnt(6)
	v_mfma_f32_32x32x16_bf16 v[64:79], v[6:9], v[100:103], v[64:79]
	s_waitcnt lgkmcnt(5)
	v_mfma_f32_32x32x16_bf16 v[48:63], v[10:13], v[88:91], 0
	s_waitcnt lgkmcnt(4)
	s_nop 8
	v_add_f32_e32 v1, v64, v2
	v_add_u32_e32 v10, 3, v15
	v_add_f32_e32 v2, v65, v3
	v_cndmask_b32_e32 v1, v1, v164, vcc
	s_and_b64 vcc, s[60:61], s[18:19]
	v_add_u32_e32 v11, 8, v15
	v_cmp_gt_i32_e64 s[24:25], v10, v134
	v_add_f32_e32 v3, v66, v4
	v_cndmask_b32_e32 v10, v2, v164, vcc
	s_and_b64 vcc, s[60:61], s[20:21]
	v_cmp_gt_i32_e64 s[26:27], v11, v134
	v_add_f32_e32 v4, v67, v5
	v_cndmask_b32_e32 v12, v3, v164, vcc
	s_and_b64 vcc, s[60:61], s[24:25]
	s_waitcnt lgkmcnt(3)
	v_add_f32_e32 v5, v68, v168
	v_cndmask_b32_e32 v13, v4, v164, vcc
	s_and_b64 vcc, s[60:61], s[26:27]
	v_cndmask_b32_e32 v64, v5, v164, vcc
	v_cmp_ge_i32_e32 vcc, v11, v134
	v_add_f32_e32 v3, v69, v169
	s_and_b64 vcc, s[60:61], vcc
	v_max3_f32 v2, v1, s67, v10
	v_cndmask_b32_e32 v11, v3, v164, vcc
	v_add_u32_e32 v3, 10, v15
	v_max3_f32 v2, v2, v12, v13
	v_cmp_gt_i32_e32 vcc, v3, v134
	v_max3_f32 v6, v2, v64, v11
	v_add_f32_e32 v2, v70, v170
	s_and_b64 vcc, s[60:61], vcc
	v_cndmask_b32_e32 v65, v2, v164, vcc
	v_add_u32_e32 v2, 11, v15
	v_cmp_gt_i32_e32 vcc, v2, v134
	ds_read_b128 v[2:5], v14 offset:68
	s_waitcnt lgkmcnt(3)
	v_mfma_f32_32x32x16_bf16 v[48:63], v[172:175], v[92:95], v[48:63]
	v_add_f32_e32 v7, v71, v171
	s_and_b64 vcc, s[60:61], vcc
	v_add_u32_e32 v68, 16, v15
	v_cndmask_b32_e32 v66, v7, v164, vcc
	v_cmp_gt_i32_e32 vcc, v68, v134
	v_max3_f32 v67, v6, v65, v66
	ds_read_b128 v[6:9], v14 offset:100
	s_waitcnt lgkmcnt(1)
	v_add_f32_e32 v2, v72, v2
	s_and_b64 vcc, s[60:61], vcc
	v_cndmask_b32_e32 v69, v2, v164, vcc
	v_cmp_ge_i32_e32 vcc, v68, v134
	v_add_f32_e32 v2, v73, v3
	s_and_b64 vcc, s[60:61], vcc
	v_add_f32_e32 v3, v74, v4
	v_add_u32_e32 v4, 18, v15
	v_cndmask_b32_e32 v68, v2, v164, vcc
	v_cmp_gt_i32_e32 vcc, v4, v134
	v_mfma_f32_32x32x16_bf16 v[48:63], v[176:179], v[96:99], v[48:63]
	s_and_b64 vcc, s[60:61], vcc
	v_add_u32_e32 v4, 19, v15
	v_max3_f32 v2, v67, v69, v68
	v_cndmask_b32_e32 v67, v3, v164, vcc
	v_cmp_gt_i32_e32 vcc, v4, v134
	v_add_f32_e32 v3, v75, v5
	s_and_b64 vcc, s[60:61], vcc
	v_cndmask_b32_e32 v70, v3, v164, vcc
	v_add_u32_e32 v3, 24, v15
	v_cmp_gt_i32_e32 vcc, v3, v134
	s_waitcnt lgkmcnt(0)
	v_add_f32_e32 v4, v76, v6
	s_and_b64 vcc, s[60:61], vcc
	v_cndmask_b32_e32 v71, v4, v164, vcc
	v_cmp_ge_i32_e32 vcc, v3, v134
	v_add_f32_e32 v4, v77, v7
	s_and_b64 vcc, s[60:61], vcc
	v_add_u32_e32 v3, 26, v15
	v_mfma_f32_32x32x16_bf16 v[48:63], v[180:183], v[100:103], v[48:63]
	v_max3_f32 v2, v2, v67, v70
	v_cndmask_b32_e32 v72, v4, v164, vcc
	v_cmp_gt_i32_e32 vcc, v3, v134
	v_max3_f32 v6, v2, v71, v72
	v_add_f32_e32 v2, v78, v8
	s_and_b64 vcc, s[60:61], vcc
	v_cndmask_b32_e32 v73, v2, v164, vcc
	v_add_u32_e32 v2, 27, v15
	v_cmp_gt_i32_e32 vcc, v2, v134
	ds_read_b128 v[2:5], v14 offset:132
	v_add_f32_e32 v7, v79, v9
	s_and_b64 vcc, s[60:61], vcc
	v_add_u32_e32 v76, 32, v15
	v_cndmask_b32_e32 v74, v7, v164, vcc
	v_cmp_gt_i32_e32 vcc, v76, v134
	v_max3_f32 v75, v6, v73, v74
	ds_read_b128 v[6:9], v14 offset:164
	s_waitcnt lgkmcnt(1)
	v_add_f32_e32 v2, v48, v2
	s_and_b64 vcc, s[60:61], vcc
	v_cndmask_b32_e32 v48, v2, v164, vcc
	v_cmp_ge_i32_e32 vcc, v76, v134
	v_add_f32_e32 v2, v49, v3
	s_and_b64 vcc, s[60:61], vcc
	v_add_f32_e32 v3, v50, v4
	v_add_u32_e32 v4, 34, v15
	v_cndmask_b32_e32 v49, v2, v164, vcc
	v_cmp_gt_i32_e32 vcc, v4, v134
	s_and_b64 vcc, s[60:61], vcc
	v_add_u32_e32 v4, 35, v15
	v_cndmask_b32_e32 v50, v3, v164, vcc
	v_cmp_gt_i32_e32 vcc, v4, v134
	v_add_f32_e32 v3, v51, v5
	s_and_b64 vcc, s[60:61], vcc
	v_cndmask_b32_e32 v51, v3, v164, vcc
	v_add_u32_e32 v3, 40, v15
	v_cmp_gt_i32_e32 vcc, v3, v134
	s_waitcnt lgkmcnt(0)
	v_add_f32_e32 v4, v52, v6
	s_and_b64 vcc, s[60:61], vcc
	v_cndmask_b32_e32 v52, v4, v164, vcc
	v_cmp_ge_i32_e32 vcc, v3, v134
	v_max3_f32 v2, v75, v48, v49
	v_add_f32_e32 v4, v53, v7
	s_and_b64 vcc, s[60:61], vcc
	v_add_u32_e32 v3, 42, v15
	v_max3_f32 v2, v2, v50, v51
	v_cndmask_b32_e32 v53, v4, v164, vcc
	v_cmp_gt_i32_e32 vcc, v3, v134
	v_max3_f32 v6, v2, v52, v53
	v_add_f32_e32 v2, v54, v8
	s_and_b64 vcc, s[60:61], vcc
	v_cndmask_b32_e32 v54, v2, v164, vcc
	v_add_u32_e32 v2, 43, v15
	v_cmp_gt_i32_e32 vcc, v2, v134
	ds_read_b128 v[2:5], v14 offset:196
	v_add_f32_e32 v7, v55, v9
	s_and_b64 vcc, s[60:61], vcc
	v_add_u32_e32 v76, 48, v15
	v_cndmask_b32_e32 v55, v7, v164, vcc
	v_cmp_gt_i32_e32 vcc, v76, v134
	v_max3_f32 v75, v6, v54, v55
	ds_read_b128 v[6:9], v14 offset:228
	s_waitcnt lgkmcnt(1)
; #define LAS __attribute__((address_space(3)))
; __device__ __forceinline__ float fexp2(float x) { return __builtin_amdgcn_exp2f(x); }
; __device__ __forceinline__ void attn_phase(LAS unsigned char* lds, const int wid, const bf16_t* P, const float* LF, bf16_t* CAT, const float* qgain, const float* kgain) {
;     ...
;                                 float sv = sacc[kb][4 * i4 + jj] + bias[jj];
;                                 if (diag && (kt * 64 + kl + jj > qrow)) sv = -1e30f;
;                                 sacc[kb][4 * i4 + jj] = sv; mloc = fmaxf(mloc, sv);
;                             }
;                         }
;                     mloc = fmaxf(mloc, __shfl_xor(mloc, 32));
;                     const float mnew = fmaxf(mrun, mloc);
;                     const float alpha = fexp2(mrun - mnew); mrun = mnew;
;                     float ps = 0.f;
; #pragma unroll
;                     for (int kb = 0; kb < 2; ++kb)
; #pragma unroll
;                         for (int i = 0; i < 16; ++i) { const float p = fexp2(sacc[kb][i] - mnew); sacc[kb][i] = p; ps += p; }
;                     lsum = lsum * alpha + ps;
; #pragma unroll
;                     for (int i = 0; i < 16; ++i) { O[0][i] *= alpha; O[1][i] *= alpha; }
; #pragma unroll
;                     for (int kb = 0; kb < 2; ++kb)
; #pragma unroll
;                         for (int s2 = 0; s2 < 2; ++s2) {
;                             u32x4 pw; pw.x = cvt_pk_bf16(sacc[kb][8 * s2 + 0], sacc[kb][8 * s2 + 1]); pw.y = cvt_pk_bf16(sacc[kb][8 * s2 + 2], sacc[kb][8 * s2 + 3]);
;                             pw.z = cvt_pk_bf16(sacc[kb][8 * s2 + 4], sacc[kb][8 * s2 + 5]); pw.w = cvt_pk_bf16(sacc[kb][8 * s2 + 6], sacc[kb][8 * s2 + 7]);
;                             const bf16x8 pf = __builtin_bit_cast(bf16x8, pw);
; #pragma unroll
;                             for (int db = 0; db < 2; ++db) {
;                                 const LAS unsigned char* vp = vb_ + (db * 32 + r32) * VPITCH + (kb * 32 + 16 * s2 + 4 * hh) * 2;
;                                 const s16x4 lo = *(const LAS s16x4*)vp, hi = *(const LAS s16x4*)(vp + 16);
;                                 const bf16x8 av = __builtin_shufflevector(lo, hi, 0, 1, 2, 3, 4, 5, 6, 7);
;                                 O[db] = __builtin_amdgcn_mfma_f32_32x32x16_bf16(av, pf, O[db], 0, 0, 0);
;                             }
	v_add_f32_e32 v2, v56, v2
	s_and_b64 vcc, s[60:61], vcc
	v_cndmask_b32_e32 v56, v2, v164, vcc
	v_cmp_ge_i32_e32 vcc, v76, v134
	v_add_f32_e32 v2, v57, v3
	s_and_b64 vcc, s[60:61], vcc
	v_add_f32_e32 v3, v58, v4
	v_add_u32_e32 v4, 50, v15
	v_cndmask_b32_e32 v57, v2, v164, vcc
	v_cmp_gt_i32_e32 vcc, v4, v134
	s_and_b64 vcc, s[60:61], vcc
	v_add_u32_e32 v4, 51, v15
	v_cndmask_b32_e32 v58, v3, v164, vcc
	v_cmp_gt_i32_e32 vcc, v4, v134
	v_add_f32_e32 v3, v59, v5
	s_and_b64 vcc, s[60:61], vcc
	v_cndmask_b32_e32 v59, v3, v164, vcc
	v_add_u32_e32 v3, 56, v15
	v_cmp_gt_i32_e32 vcc, v3, v134
	s_waitcnt lgkmcnt(0)
	v_add_f32_e32 v4, v60, v6
	s_and_b64 vcc, s[60:61], vcc
	v_cndmask_b32_e32 v60, v4, v164, vcc
	v_cmp_ge_i32_e32 vcc, v3, v134
	v_add_f32_e32 v4, v61, v7
	s_and_b64 vcc, s[60:61], vcc
	v_cndmask_b32_e32 v61, v4, v164, vcc
	v_add_u32_e32 v4, 58, v15
	v_cmp_gt_i32_e32 vcc, v4, v134
	v_add_f32_e32 v3, v62, v8
	s_and_b64 vcc, s[60:61], vcc
	v_add_u32_e32 v4, 59, v15
	v_max3_f32 v2, v75, v56, v57
	v_cndmask_b32_e32 v62, v3, v164, vcc
	v_cmp_gt_i32_e32 vcc, v4, v134
	v_max3_f32 v2, v2, v58, v59
	v_add_f32_e32 v3, v63, v9
	s_and_b64 vcc, s[60:61], vcc
	v_max3_f32 v2, v2, v60, v61
	v_cndmask_b32_e32 v15, v3, v164, vcc
	v_max3_f32 v2, v2, v62, v15
	ds_bpermute_b32 v3, v146, v2
	s_mul_i32 s18, s80, 0x2200
	s_waitcnt lgkmcnt(0)
	v_max3_f32 v63, v166, v2, v3
	v_sub_f32_e32 v1, v1, v63
	v_exp_f32_e32 v1, v1
	v_sub_f32_e32 v3, v10, v63
	v_exp_f32_e32 v6, v3
	v_sub_f32_e32 v3, v12, v63
	v_exp_f32_e32 v7, v3
	v_sub_f32_e32 v3, v13, v63
	v_exp_f32_e32 v8, v3
	v_sub_f32_e32 v4, v64, v63
	v_add_f32_e32 v3, 0, v1
	v_exp_f32_e32 v9, v4
	v_sub_f32_e32 v4, v11, v63
	v_add_f32_e32 v3, v6, v3
	v_exp_f32_e32 v10, v4
	v_sub_f32_e32 v4, v65, v63
	v_add_f32_e32 v3, v7, v3
	v_exp_f32_e32 v11, v4
	v_sub_f32_e32 v4, v66, v63
	v_add_f32_e32 v3, v8, v3
	v_exp_f32_e32 v12, v4
	v_sub_f32_e32 v4, v69, v63
	v_add_f32_e32 v3, v9, v3
	v_exp_f32_e32 v64, v4
	v_sub_f32_e32 v4, v68, v63
	v_add_f32_e32 v3, v10, v3
	v_exp_f32_e32 v65, v4
	v_sub_f32_e32 v4, v67, v63
	v_add_f32_e32 v3, v11, v3
	v_exp_f32_e32 v66, v4
	v_sub_f32_e32 v4, v70, v63
	v_add_f32_e32 v3, v12, v3
	v_exp_f32_e32 v67, v4
	v_sub_f32_e32 v4, v71, v63
	v_add_f32_e32 v3, v64, v3
	v_exp_f32_e32 v68, v4
	v_sub_f32_e32 v4, v72, v63
	v_add_f32_e32 v3, v65, v3
	v_exp_f32_e32 v69, v4
	v_sub_f32_e32 v4, v73, v63
	v_add_f32_e32 v3, v66, v3
	v_exp_f32_e32 v70, v4
	v_sub_f32_e32 v4, v74, v63
	v_add_f32_e32 v3, v67, v3
	v_exp_f32_e32 v71, v4
	v_sub_f32_e32 v4, v48, v63
	v_add_f32_e32 v3, v68, v3
	v_exp_f32_e32 v48, v4
	v_sub_f32_e32 v4, v49, v63
	v_add_f32_e32 v3, v69, v3
	v_exp_f32_e32 v49, v4
	v_sub_f32_e32 v4, v50, v63
	v_add_f32_e32 v3, v70, v3
	v_exp_f32_e32 v50, v4
	v_sub_f32_e32 v4, v51, v63
	v_add_f32_e32 v3, v71, v3
	v_exp_f32_e32 v51, v4
	v_sub_f32_e32 v4, v52, v63
	v_add_f32_e32 v3, v48, v3
	v_exp_f32_e32 v52, v4
	v_sub_f32_e32 v4, v53, v63
	v_add_f32_e32 v3, v49, v3
	v_exp_f32_e32 v53, v4
	v_sub_f32_e32 v4, v54, v63
	v_add_f32_e32 v3, v50, v3
	v_exp_f32_e32 v54, v4
	v_add_f32_e32 v3, v51, v3
	v_sub_f32_e32 v2, v166, v63
	v_add_f32_e32 v3, v52, v3
	v_add3_u32 v13, v161, s18, v163
	v_add_f32_e32 v3, v53, v3
	v_exp_f32_e32 v14, v2
	v_sub_f32_e32 v2, v55, v63
	v_add_u32_e32 v73, 0x8800, v13
	v_add_f32_e32 v72, v54, v3
	v_exp_f32_e32 v55, v2
	ds_read2_b64 v[2:5], v73 offset1:2
	v_cvt_pk_bf16_f32 v6, v1, v6
	v_add_u32_e32 v1, 0x9800, v13
	v_cvt_pk_bf16_f32 v7, v7, v8
	v_cvt_pk_bf16_f32 v8, v9, v10
	v_cvt_pk_bf16_f32 v9, v11, v12
	ds_read2_b64 v[10:13], v1 offset0:32 offset1:34
	v_pk_mul_f32 v[46:47], v[46:47], v[14:15] op_sel_hi:[1,0]
	v_pk_mul_f32 v[44:45], v[44:45], v[14:15] op_sel_hi:[1,0]
	v_pk_mul_f32 v[42:43], v[42:43], v[14:15] op_sel_hi:[1,0]
	v_pk_mul_f32 v[40:41], v[40:41], v[14:15] op_sel_hi:[1,0]
	v_pk_mul_f32 v[38:39], v[38:39], v[14:15] op_sel_hi:[1,0]
	v_pk_mul_f32 v[36:37], v[36:37], v[14:15] op_sel_hi:[1,0]
	v_pk_mul_f32 v[34:35], v[34:35], v[14:15] op_sel_hi:[1,0]
	v_pk_mul_f32 v[32:33], v[32:33], v[14:15] op_sel_hi:[1,0]
	v_pk_mul_f32 v[30:31], v[30:31], v[14:15] op_sel_hi:[1,0]
	v_pk_mul_f32 v[28:29], v[28:29], v[14:15] op_sel_hi:[1,0]
	s_waitcnt lgkmcnt(1)
	v_mfma_f32_32x32x16_bf16 v[32:47], v[2:5], v[6:9], v[32:47]
	ds_read2_b64 v[2:5], v73 offset0:4 offset1:6
	v_mul_f32_e64 v26, v26, v14
	v_mul_f32_e64 v27, v27, v14
	v_mul_f32_e64 v24, v24, v14
	v_mul_f32_e64 v25, v25, v14
	v_pk_mul_f32 v[22:23], v[22:23], v[14:15] op_sel_hi:[1,0]
	v_pk_mul_f32 v[20:21], v[20:21], v[14:15] op_sel_hi:[1,0]
	v_pk_mul_f32 v[18:19], v[18:19], v[14:15] op_sel_hi:[1,0]
	v_pk_mul_f32 v[16:17], v[16:17], v[14:15] op_sel_hi:[1,0]
	v_mov_b32_e32 v166, v63
	s_waitcnt lgkmcnt(1)
	v_mfma_f32_32x32x16_bf16 v[16:31], v[10:13], v[6:9], v[16:31]
	v_sub_f32_e32 v6, v56, v63
	v_exp_f32_e32 v56, v6
	ds_read2_b64 v[10:13], v1 offset0:36 offset1:38
	v_cvt_pk_bf16_f32 v6, v64, v65
	v_cvt_pk_bf16_f32 v7, v66, v67
	v_cvt_pk_bf16_f32 v8, v68, v69
	v_cvt_pk_bf16_f32 v9, v70, v71
	s_waitcnt lgkmcnt(1)
	s_nop 0
	v_mfma_f32_32x32x16_bf16 v[32:47], v[2:5], v[6:9], v[32:47]
	v_add_f32_e32 v2, v55, v72
	v_add_f32_e32 v64, v56, v2
	v_sub_f32_e32 v2, v57, v63
	v_exp_f32_e32 v57, v2
	v_sub_f32_e32 v2, v58, v63
	v_exp_f32_e32 v58, v2
	ds_read2_b64 v[2:5], v73 offset0:8 offset1:10
	s_waitcnt lgkmcnt(1)
	v_mfma_f32_32x32x16_bf16 v[16:31], v[10:13], v[6:9], v[16:31]
	ds_read2_b64 v[10:13], v1 offset0:40 offset1:42
	v_sub_f32_e32 v6, v59, v63
	v_exp_f32_e32 v59, v6
	v_cvt_pk_bf16_f32 v6, v48, v49
	v_cvt_pk_bf16_f32 v7, v50, v51
	v_cvt_pk_bf16_f32 v8, v52, v53
	v_cvt_pk_bf16_f32 v9, v54, v55
	s_waitcnt lgkmcnt(1)
	s_nop 0
	v_mfma_f32_32x32x16_bf16 v[32:47], v[2:5], v[6:9], v[32:47]
	v_sub_f32_e32 v2, v60, v63
	v_exp_f32_e32 v48, v2
	v_sub_f32_e32 v2, v61, v63
	v_exp_f32_e32 v49, v2
	v_sub_f32_e32 v2, v62, v63
	v_exp_f32_e32 v50, v2
	ds_read2_b64 v[2:5], v73 offset0:12 offset1:14
	s_waitcnt lgkmcnt(1)
	v_mfma_f32_32x32x16_bf16 v[16:31], v[10:13], v[6:9], v[16:31]
	ds_read2_b64 v[10:13], v1 offset0:44 offset1:46
	v_sub_f32_e32 v6, v15, v63
	v_exp_f32_e32 v15, v6
	v_cvt_pk_bf16_f32 v6, v56, v57
	v_cvt_pk_bf16_f32 v7, v58, v59
	v_cvt_pk_bf16_f32 v8, v48, v49
	v_cvt_pk_bf16_f32 v9, v50, v15
	v_add_f32_e32 v1, v57, v64
	v_add_f32_e32 v1, v58, v1
	s_waitcnt lgkmcnt(1)
	v_mfma_f32_32x32x16_bf16 v[32:47], v[2:5], v[6:9], v[32:47]
	v_add_f32_e32 v1, v59, v1
	v_add_f32_e32 v1, v48, v1
	v_add_f32_e32 v1, v49, v1
	v_add_f32_e32 v1, v50, v1
	v_add_f32_e32 v1, v15, v1
	v_fmac_f32_e32 v1, v135, v14
	v_mov_b32_e32 v135, v1
	s_waitcnt lgkmcnt(0)
	v_mfma_f32_32x32x16_bf16 v[16:31], v[10:13], v[6:9], v[16:31]

; #define LAS __attribute__((address_space(3)))
; __device__ __forceinline__ void attn_phase(LAS unsigned char* lds, const int wid, const bf16_t* P, const float* LF, bf16_t* CAT, const float* qgain, const float* kgain) {
;     ...
;                 if (kt * 64 <= q0 + 31 && !done_w) {
;                     const LAS unsigned char* kb_ = KB + cb * 64 * KPITCH;
;                     const LAS unsigned char* vb_ = VB + cb * 64 * VPITCH;
;                     f32x16 sacc[2];
; #pragma unroll
;                     for (int kb = 0; kb < 2; ++kb) {
; #pragma unroll
;                         for (int i = 0; i < 16; ++i) sacc[kb][i] = 0.f;
; #pragma unroll
;                         for (int ds = 0; ds < 4; ++ds) {
;                             const bf16x8 a = *(const LAS bf16x8*)(kb_ + (kb * 32 + r32) * KPITCH + (16 * ds + 8 * hh) * 2);
;                             sacc[kb] = __builtin_amdgcn_mfma_f32_32x32x16_bf16(a, qf[ds], sacc[kb], 0, 0, 0);
;                         }
;                     }
;                     const bool diag = (kt * 64 + 63 > q0);
;                     float mloc = -1e30f;
; #pragma unroll
;                     for (int kb = 0; kb < 2; ++kb)
; #pragma unroll
;                         for (int i4 = 0; i4 < 4; ++i4) {
;                             const int kl = kb * 32 + 8 * i4 + 4 * hh;
;                             const f32x4 bias = *(const LAS f32x4*)(CB + kt * 64 + kl);
; #pragma unroll
;                             for (int jj = 0; jj < 4; ++jj) {
;                                 float sv = sacc[kb][4 * i4 + jj] + bias[jj];
;                                 if (diag && (kt * 64 + kl + jj > qrow)) sv = -1e30f;
;                                 sacc[kb][4 * i4 + jj] = sv; mloc = fmaxf(mloc, sv);
;                             }
;                         }
;                     mloc = fmaxf(mloc, __shfl_xor(mloc, 32));
.Lattn_nodiag_a:
	s_mul_i32 s18, s80, 0x2400
	v_add3_u32 v1, v160, s18, v162
	ds_read_b128 v[2:5], v1 offset:16384
	ds_read_b128 v[6:9], v1 offset:16416
	v_add_u32_e32 v14, s78, v159
	s_add_i32 s18, s77, 63
	v_add_u32_e32 v15, s77, v112
	s_waitcnt lgkmcnt(1)
	v_mfma_f32_32x32x16_bf16 v[64:79], v[2:5], v[88:91], 0
	ds_read_b128 v[2:5], v1 offset:16448
	s_cmp_gt_i32 s18, s74
	s_cselect_b64 s[60:61], -1, 0
	s_waitcnt lgkmcnt(1)
	v_mfma_f32_32x32x16_bf16 v[64:79], v[6:9], v[92:95], v[64:79]
	ds_read_b128 v[6:9], v1 offset:16480
	ds_read_b128 v[10:13], v1 offset:20992
	s_waitcnt lgkmcnt(2)
	v_mfma_f32_32x32x16_bf16 v[64:79], v[2:5], v[96:99], v[64:79]
	ds_read_b128 v[2:5], v14 offset:4
	ds_read_b128 v[168:171], v14 offset:36
	ds_read_b128 v[172:175], v1 offset:21024
	ds_read_b128 v[176:179], v1 offset:21056
	ds_read_b128 v[180:183], v1 offset:21088
	s_waitcnt lgkmcnt(6)
	v_mfma_f32_32x32x16_bf16 v[64:79], v[6:9], v[100:103], v[64:79]
	s_waitcnt lgkmcnt(5)
	v_mfma_f32_32x32x16_bf16 v[48:63], v[10:13], v[88:91], 0
	s_waitcnt lgkmcnt(4)
	s_nop 8
	v_add_f32_e32 v1, v64, v2
	v_add_f32_e32 v10, v65, v3
	v_add_f32_e32 v12, v66, v4
	v_add_f32_e32 v13, v67, v5
	s_waitcnt lgkmcnt(3)
	v_add_f32_e32 v64, v68, v168
	v_add_f32_e32 v11, v69, v169
	v_max3_f32 v2, v1, s67, v10
	v_max3_f32 v2, v2, v12, v13
	v_max3_f32 v6, v2, v64, v11
	v_add_f32_e32 v65, v70, v170
	ds_read_b128 v[2:5], v14 offset:68
	s_waitcnt lgkmcnt(3)
	v_mfma_f32_32x32x16_bf16 v[48:63], v[172:175], v[92:95], v[48:63]
	v_add_f32_e32 v66, v71, v171
	v_max3_f32 v67, v6, v65, v66
	ds_read_b128 v[6:9], v14 offset:100
	s_waitcnt lgkmcnt(1)
	v_add_f32_e32 v69, v72, v2
	v_add_f32_e32 v68, v73, v3
	v_add_f32_e32 v3, v74, v4
	v_mfma_f32_32x32x16_bf16 v[48:63], v[176:179], v[96:99], v[48:63]
	v_max3_f32 v2, v67, v69, v68
	v_mov_b32_e32 v67, v3
	v_add_f32_e32 v70, v75, v5
	s_waitcnt lgkmcnt(0)
	v_add_f32_e32 v71, v76, v6
	v_add_f32_e32 v72, v77, v7
	v_mfma_f32_32x32x16_bf16 v[48:63], v[180:183], v[100:103], v[48:63]
	v_max3_f32 v2, v2, v67, v70
	v_max3_f32 v6, v2, v71, v72
	v_add_f32_e32 v73, v78, v8
	ds_read_b128 v[2:5], v14 offset:132
	v_add_f32_e32 v74, v79, v9
	v_max3_f32 v75, v6, v73, v74
	ds_read_b128 v[6:9], v14 offset:164
	s_waitcnt lgkmcnt(1)
	s_nop 3
	v_add_f32_e32 v2, v48, v2
	v_mov_b32_e32 v48, v2
	v_add_f32_e32 v2, v49, v3
	v_add_f32_e32 v3, v50, v4
	v_mov_b32_e32 v49, v2
	v_mov_b32_e32 v50, v3
	v_add_f32_e32 v3, v51, v5
	v_mov_b32_e32 v51, v3
	s_waitcnt lgkmcnt(0)
	v_add_f32_e32 v4, v52, v6
	v_mov_b32_e32 v52, v4
	v_max3_f32 v2, v75, v48, v49
	v_add_f32_e32 v4, v53, v7
	v_max3_f32 v2, v2, v50, v51
	v_mov_b32_e32 v53, v4
	v_max3_f32 v6, v2, v52, v53
	v_add_f32_e32 v2, v54, v8
	v_mov_b32_e32 v54, v2
	ds_read_b128 v[2:5], v14 offset:196
	v_add_f32_e32 v7, v55, v9
	v_add_u32_e32 v76, 48, v15
	v_mov_b32_e32 v55, v7
	v_max3_f32 v75, v6, v54, v55
	ds_read_b128 v[6:9], v14 offset:228
	s_waitcnt lgkmcnt(1)
	v_add_f32_e32 v2, v56, v2
	v_mov_b32_e32 v56, v2
	v_add_f32_e32 v2, v57, v3
	v_add_f32_e32 v3, v58, v4
	v_mov_b32_e32 v57, v2
	v_mov_b32_e32 v58, v3
	v_add_f32_e32 v3, v59, v5
	v_mov_b32_e32 v59, v3
	s_waitcnt lgkmcnt(0)
	v_add_f32_e32 v4, v60, v6
	v_mov_b32_e32 v60, v4
	v_add_f32_e32 v4, v61, v7
	v_mov_b32_e32 v61, v4
	v_add_f32_e32 v3, v62, v8
	v_max3_f32 v2, v75, v56, v57
	v_mov_b32_e32 v62, v3
	v_max3_f32 v2, v2, v58, v59
	v_add_f32_e32 v15, v63, v9
	v_max3_f32 v2, v2, v60, v61
	v_max3_f32 v2, v2, v62, v15
	ds_bpermute_b32 v3, v146, v2
	s_mul_i32 s18, s80, 0x2200
	s_waitcnt lgkmcnt(0)
; #define LAS __attribute__((address_space(3)))
; __device__ __forceinline__ unsigned cvt_pk_bf16(float lo, float hi) { const f32x2 v = {lo, hi}; return __builtin_bit_cast(unsigned, __builtin_convertvector(v, b16x2_t)); }
; __device__ __forceinline__ float fexp2(float x) { return __builtin_amdgcn_exp2f(x); }
; __device__ __forceinline__ void attn_phase(LAS unsigned char* lds, const int wid, const bf16_t* P, const float* LF, bf16_t* CAT, const float* qgain, const float* kgain) {
;     ...
;                     mloc = fmaxf(mloc, __shfl_xor(mloc, 32));
;                     const float mnew = fmaxf(mrun, mloc);
;                     const float alpha = fexp2(mrun - mnew); mrun = mnew;
;                     float ps = 0.f;
; #pragma unroll
;                     for (int kb = 0; kb < 2; ++kb)
; #pragma unroll
;                         for (int i = 0; i < 16; ++i) { const float p = fexp2(sacc[kb][i] - mnew); sacc[kb][i] = p; ps += p; }
;                     lsum = lsum * alpha + ps;
; #pragma unroll
;                     for (int i = 0; i < 16; ++i) { O[0][i] *= alpha; O[1][i] *= alpha; }
; #pragma unroll
;                     for (int kb = 0; kb < 2; ++kb)
; #pragma unroll
;                         for (int s2 = 0; s2 < 2; ++s2) {
;                             u32x4 pw; pw.x = cvt_pk_bf16(sacc[kb][8 * s2 + 0], sacc[kb][8 * s2 + 1]); pw.y = cvt_pk_bf16(sacc[kb][8 * s2 + 2], sacc[kb][8 * s2 + 3]);
;                             pw.z = cvt_pk_bf16(sacc[kb][8 * s2 + 4], sacc[kb][8 * s2 + 5]); pw.w = cvt_pk_bf16(sacc[kb][8 * s2 + 6], sacc[kb][8 * s2 + 7]);
;                             const bf16x8 pf = __builtin_bit_cast(bf16x8, pw);
; #pragma unroll
;                             for (int db = 0; db < 2; ++db) {
;                                 const LAS unsigned char* vp = vb_ + (db * 32 + r32) * VPITCH + (kb * 32 + 16 * s2 + 4 * hh) * 2;
;                                 const s16x4 lo = *(const LAS s16x4*)vp, hi = *(const LAS s16x4*)(vp + 16);
;                                 const bf16x8 av = __builtin_shufflevector(lo, hi, 0, 1, 2, 3, 4, 5, 6, 7);
;                                 O[db] = __builtin_amdgcn_mfma_f32_32x32x16_bf16(av, pf, O[db], 0, 0, 0);
;                             }
;                         }
;                 }
	v_max3_f32 v63, v166, v2, v3
	v_sub_f32_e32 v1, v1, v63
	v_exp_f32_e32 v1, v1
	v_sub_f32_e32 v3, v10, v63
	v_exp_f32_e32 v6, v3
	v_sub_f32_e32 v3, v12, v63
	v_exp_f32_e32 v7, v3
	v_sub_f32_e32 v3, v13, v63
	v_exp_f32_e32 v8, v3
	v_sub_f32_e32 v4, v64, v63
	v_add_f32_e32 v3, 0, v1
	v_exp_f32_e32 v9, v4
	v_sub_f32_e32 v4, v11, v63
	v_add_f32_e32 v3, v6, v3
	v_exp_f32_e32 v10, v4
	v_sub_f32_e32 v4, v65, v63
	v_add_f32_e32 v3, v7, v3
	v_exp_f32_e32 v11, v4
	v_sub_f32_e32 v4, v66, v63
	v_add_f32_e32 v3, v8, v3
	v_exp_f32_e32 v12, v4
	v_sub_f32_e32 v4, v69, v63
	v_add_f32_e32 v3, v9, v3
	v_exp_f32_e32 v64, v4
	v_sub_f32_e32 v4, v68, v63
	v_add_f32_e32 v3, v10, v3
	v_exp_f32_e32 v65, v4
	v_sub_f32_e32 v4, v67, v63
	v_add_f32_e32 v3, v11, v3
	v_exp_f32_e32 v66, v4
	v_sub_f32_e32 v4, v70, v63
	v_add_f32_e32 v3, v12, v3
	v_exp_f32_e32 v67, v4
	v_sub_f32_e32 v4, v71, v63
	v_add_f32_e32 v3, v64, v3
	v_exp_f32_e32 v68, v4
	v_sub_f32_e32 v4, v72, v63
	v_add_f32_e32 v3, v65, v3
	v_exp_f32_e32 v69, v4
	v_sub_f32_e32 v4, v73, v63
	v_add_f32_e32 v3, v66, v3
	v_exp_f32_e32 v70, v4
	v_sub_f32_e32 v4, v74, v63
	v_add_f32_e32 v3, v67, v3
	v_exp_f32_e32 v71, v4
	v_sub_f32_e32 v4, v48, v63
	v_add_f32_e32 v3, v68, v3
	v_exp_f32_e32 v48, v4
	v_sub_f32_e32 v4, v49, v63
	v_add_f32_e32 v3, v69, v3
	v_exp_f32_e32 v49, v4
	v_sub_f32_e32 v4, v50, v63
	v_add_f32_e32 v3, v70, v3
	v_exp_f32_e32 v50, v4
	v_sub_f32_e32 v4, v51, v63
	v_add_f32_e32 v3, v71, v3
	v_exp_f32_e32 v51, v4
	v_sub_f32_e32 v4, v52, v63
	v_add_f32_e32 v3, v48, v3
	v_exp_f32_e32 v52, v4
	v_sub_f32_e32 v4, v53, v63
	v_add_f32_e32 v3, v49, v3
	v_exp_f32_e32 v53, v4
	v_sub_f32_e32 v4, v54, v63
	v_add_f32_e32 v3, v50, v3
	v_exp_f32_e32 v54, v4
	v_add_f32_e32 v3, v51, v3
	v_sub_f32_e32 v2, v166, v63
	v_add_f32_e32 v3, v52, v3
	v_add3_u32 v13, v161, s18, v163
	v_add_f32_e32 v3, v53, v3
	v_exp_f32_e32 v14, v2
	v_sub_f32_e32 v2, v55, v63
	v_add_u32_e32 v73, 0x8800, v13
	v_add_f32_e32 v72, v54, v3
	v_exp_f32_e32 v55, v2
	ds_read2_b64 v[2:5], v73 offset1:2
	v_cvt_pk_bf16_f32 v6, v1, v6
	v_add_u32_e32 v1, 0x9800, v13
	v_cvt_pk_bf16_f32 v7, v7, v8
	v_cvt_pk_bf16_f32 v8, v9, v10
	v_cvt_pk_bf16_f32 v9, v11, v12
	ds_read2_b64 v[10:13], v1 offset0:32 offset1:34
	v_pk_mul_f32 v[46:47], v[46:47], v[14:15] op_sel_hi:[1,0]
	v_pk_mul_f32 v[44:45], v[44:45], v[14:15] op_sel_hi:[1,0]
	v_pk_mul_f32 v[42:43], v[42:43], v[14:15] op_sel_hi:[1,0]
	v_pk_mul_f32 v[40:41], v[40:41], v[14:15] op_sel_hi:[1,0]
	v_pk_mul_f32 v[38:39], v[38:39], v[14:15] op_sel_hi:[1,0]
	v_pk_mul_f32 v[36:37], v[36:37], v[14:15] op_sel_hi:[1,0]
	v_pk_mul_f32 v[34:35], v[34:35], v[14:15] op_sel_hi:[1,0]
	v_pk_mul_f32 v[32:33], v[32:33], v[14:15] op_sel_hi:[1,0]
	v_pk_mul_f32 v[30:31], v[30:31], v[14:15] op_sel_hi:[1,0]
	v_pk_mul_f32 v[28:29], v[28:29], v[14:15] op_sel_hi:[1,0]
	s_waitcnt lgkmcnt(1)
	v_mfma_f32_32x32x16_bf16 v[32:47], v[2:5], v[6:9], v[32:47]
	ds_read2_b64 v[2:5], v73 offset0:4 offset1:6
	v_mul_f32_e64 v26, v26, v14
	v_mul_f32_e64 v27, v27, v14
	v_mul_f32_e64 v24, v24, v14
	v_mul_f32_e64 v25, v25, v14
	v_pk_mul_f32 v[22:23], v[22:23], v[14:15] op_sel_hi:[1,0]
	v_pk_mul_f32 v[20:21], v[20:21], v[14:15] op_sel_hi:[1,0]
	v_pk_mul_f32 v[18:19], v[18:19], v[14:15] op_sel_hi:[1,0]
	v_pk_mul_f32 v[16:17], v[16:17], v[14:15] op_sel_hi:[1,0]
	v_mov_b32_e32 v166, v63
	s_waitcnt lgkmcnt(1)
	v_mfma_f32_32x32x16_bf16 v[16:31], v[10:13], v[6:9], v[16:31]
	v_sub_f32_e32 v6, v56, v63
	v_exp_f32_e32 v56, v6
	ds_read2_b64 v[10:13], v1 offset0:36 offset1:38
	v_cvt_pk_bf16_f32 v6, v64, v65
	v_cvt_pk_bf16_f32 v7, v66, v67
	v_cvt_pk_bf16_f32 v8, v68, v69
	v_cvt_pk_bf16_f32 v9, v70, v71
	s_waitcnt lgkmcnt(1)
	s_nop 0
	v_mfma_f32_32x32x16_bf16 v[32:47], v[2:5], v[6:9], v[32:47]
	v_add_f32_e32 v2, v55, v72
	v_add_f32_e32 v64, v56, v2
	v_sub_f32_e32 v2, v57, v63
	v_exp_f32_e32 v57, v2
	v_sub_f32_e32 v2, v58, v63
	v_exp_f32_e32 v58, v2
	ds_read2_b64 v[2:5], v73 offset0:8 offset1:10
	s_waitcnt lgkmcnt(1)
	v_mfma_f32_32x32x16_bf16 v[16:31], v[10:13], v[6:9], v[16:31]
	ds_read2_b64 v[10:13], v1 offset0:40 offset1:42
	v_sub_f32_e32 v6, v59, v63
	v_exp_f32_e32 v59, v6
	v_cvt_pk_bf16_f32 v6, v48, v49
	v_cvt_pk_bf16_f32 v7, v50, v51
	v_cvt_pk_bf16_f32 v8, v52, v53
	v_cvt_pk_bf16_f32 v9, v54, v55
	s_waitcnt lgkmcnt(1)
	s_nop 0
	v_mfma_f32_32x32x16_bf16 v[32:47], v[2:5], v[6:9], v[32:47]
	v_sub_f32_e32 v2, v60, v63
	v_exp_f32_e32 v48, v2
	v_sub_f32_e32 v2, v61, v63
	v_exp_f32_e32 v49, v2
	v_sub_f32_e32 v2, v62, v63
	v_exp_f32_e32 v50, v2
	ds_read2_b64 v[2:5], v73 offset0:12 offset1:14
	s_waitcnt lgkmcnt(1)
	v_mfma_f32_32x32x16_bf16 v[16:31], v[10:13], v[6:9], v[16:31]
	ds_read2_b64 v[10:13], v1 offset0:44 offset1:46
	v_sub_f32_e32 v6, v15, v63
	v_exp_f32_e32 v15, v6
	v_cvt_pk_bf16_f32 v6, v56, v57
	v_cvt_pk_bf16_f32 v7, v58, v59
	v_cvt_pk_bf16_f32 v8, v48, v49
	v_cvt_pk_bf16_f32 v9, v50, v15
	v_add_f32_e32 v1, v57, v64
	v_add_f32_e32 v1, v58, v1
	s_waitcnt lgkmcnt(1)
	v_mfma_f32_32x32x16_bf16 v[32:47], v[2:5], v[6:9], v[32:47]
	v_add_f32_e32 v1, v59, v1
	v_add_f32_e32 v1, v48, v1
	v_add_f32_e32 v1, v49, v1
	v_add_f32_e32 v1, v50, v1
	v_add_f32_e32 v1, v15, v1
	v_fmac_f32_e32 v1, v135, v14
	v_mov_b32_e32 v135, v1
	s_waitcnt lgkmcnt(0)
	v_mfma_f32_32x32x16_bf16 v[16:31], v[10:13], v[6:9], v[16:31]
	s_branch .LBB0_270

; #define LAS __attribute__((address_space(3)))
; __device__ __forceinline__ void attn_phase(LAS unsigned char* lds, const int wid, const bf16_t* P, const float* LF, bf16_t* CAT, const float* qgain, const float* kgain) {
;     ...
;                 if (kt * 64 <= q0 + 31 && !done_w) {
;                     const LAS unsigned char* kb_ = KB + cb * 64 * KPITCH;
;                     const LAS unsigned char* vb_ = VB + cb * 64 * VPITCH;
;                     f32x16 sacc[2];
; #pragma unroll
;                     for (int kb = 0; kb < 2; ++kb) {
; #pragma unroll
;                         for (int i = 0; i < 16; ++i) sacc[kb][i] = 0.f;
; #pragma unroll
;                         for (int ds = 0; ds < 4; ++ds) {
;                             const bf16x8 a = *(const LAS bf16x8*)(kb_ + (kb * 32 + r32) * KPITCH + (16 * ds + 8 * hh) * 2);
;                             sacc[kb] = __builtin_amdgcn_mfma_f32_32x32x16_bf16(a, qf[ds], sacc[kb], 0, 0, 0);
;                         }
;                     }
;                     const bool diag = (kt * 64 + 63 > q0);
;                     float mloc = -1e30f;
; #pragma unroll
;                     for (int kb = 0; kb < 2; ++kb)
; #pragma unroll
;                         for (int i4 = 0; i4 < 4; ++i4) {
;                             const int kl = kb * 32 + 8 * i4 + 4 * hh;
;                             const f32x4 bias = *(const LAS f32x4*)(CB + kt * 64 + kl);
; #pragma unroll
;                             for (int jj = 0; jj < 4; ++jj) {
;                                 float sv = sacc[kb][4 * i4 + jj] + bias[jj];
;                                 if (diag && (kt * 64 + kl + jj > qrow)) sv = -1e30f;
;                                 sacc[kb][4 * i4 + jj] = sv; mloc = fmaxf(mloc, sv);
;                             }
;                         }
.LBB0_1900:
	s_and_b32 s80, s20, 1
	s_cmp_le_i32 s77, s76
	s_cselect_b64 s[18:19], -1, 0
	v_cmp_eq_u32_e32 vcc, 0, v165
	s_and_b64 s[56:57], s[18:19], vcc
	s_and_saveexec_b64 s[58:59], s[56:57]
	s_cbranch_execz .LBB0_1902
	s_add_i32 s19, s77, 63
	s_cmp_gt_i32 s19, s74
	s_cbranch_scc0 .Lattn_nodiag_b
	s_mul_i32 s0, s80, 0x2400
	v_add3_u32 v1, v160, s0, v162
	ds_read_b128 v[2:5], v1 offset:16384
	ds_read_b128 v[6:9], v1 offset:16416
	v_add_u32_e32 v14, s78, v159
	s_add_i32 s0, s77, 63
	v_add_u32_e32 v15, s77, v112
	s_waitcnt lgkmcnt(1)
	v_mfma_f32_32x32x16_bf16 v[64:79], v[2:5], v[88:91], 0
	ds_read_b128 v[2:5], v1 offset:16448
	s_cmp_gt_i32 s0, s74
	v_cmp_gt_i32_e32 vcc, v15, v134
	s_cselect_b64 s[60:61], -1, 0
	v_cmp_ge_i32_e64 s[18:19], v15, v134
	s_and_b64 vcc, s[60:61], vcc
	s_mul_i32 s0, s80, 0x2200
	s_waitcnt lgkmcnt(1)
	v_mfma_f32_32x32x16_bf16 v[64:79], v[6:9], v[92:95], v[64:79]
	ds_read_b128 v[6:9], v1 offset:16480
	ds_read_b128 v[10:13], v1 offset:20992
	s_waitcnt lgkmcnt(2)
	v_mfma_f32_32x32x16_bf16 v[64:79], v[2:5], v[96:99], v[64:79]
	ds_read_b128 v[2:5], v14 offset:4
	ds_read_b128 v[168:171], v14 offset:36
	ds_read_b128 v[172:175], v1 offset:21024
	ds_read_b128 v[176:179], v1 offset:21056
	ds_read_b128 v[180:183], v1 offset:21088
	v_add_u32_e32 v1, 2, v15
	v_cmp_gt_i32_e64 s[20:21], v1, v134
	s_waitcnt lgkmcnt(6)
	v_mfma_f32_32x32x16_bf16 v[64:79], v[6:9], v[100:103], v[64:79]
	s_waitcnt lgkmcnt(5)
	v_mfma_f32_32x32x16_bf16 v[48:63], v[10:13], v[88:91], 0
	s_waitcnt lgkmcnt(4)
	s_nop 8
	v_add_f32_e32 v1, v64, v2
	v_add_u32_e32 v10, 3, v15
	v_add_f32_e32 v2, v65, v3
	v_cndmask_b32_e32 v1, v1, v164, vcc
	s_and_b64 vcc, s[60:61], s[18:19]
	v_add_u32_e32 v11, 8, v15
	v_cmp_gt_i32_e64 s[24:25], v10, v134
	v_add_f32_e32 v3, v66, v4
	v_cndmask_b32_e32 v10, v2, v164, vcc
	s_and_b64 vcc, s[60:61], s[20:21]
	v_cmp_gt_i32_e64 s[26:27], v11, v134
	v_add_f32_e32 v4, v67, v5
	v_cndmask_b32_e32 v12, v3, v164, vcc
	s_and_b64 vcc, s[60:61], s[24:25]
	s_waitcnt lgkmcnt(3)
	v_add_f32_e32 v5, v68, v168
	v_cndmask_b32_e32 v13, v4, v164, vcc
	s_and_b64 vcc, s[60:61], s[26:27]
	v_cndmask_b32_e32 v64, v5, v164, vcc
	v_cmp_ge_i32_e32 vcc, v11, v134
	v_add_f32_e32 v3, v69, v169
	s_and_b64 vcc, s[60:61], vcc
	v_max3_f32 v2, v1, s67, v10
	v_cndmask_b32_e32 v11, v3, v164, vcc
	v_add_u32_e32 v3, 10, v15
	v_max3_f32 v2, v2, v12, v13
	v_cmp_gt_i32_e32 vcc, v3, v134
	v_max3_f32 v6, v2, v64, v11
	v_add_f32_e32 v2, v70, v170
	s_and_b64 vcc, s[60:61], vcc
	v_cndmask_b32_e32 v65, v2, v164, vcc
	v_add_u32_e32 v2, 11, v15
	v_cmp_gt_i32_e32 vcc, v2, v134
	ds_read_b128 v[2:5], v14 offset:68
	s_waitcnt lgkmcnt(3)
	v_mfma_f32_32x32x16_bf16 v[48:63], v[172:175], v[92:95], v[48:63]
	v_add_f32_e32 v7, v71, v171
	s_and_b64 vcc, s[60:61], vcc
	v_add_u32_e32 v68, 16, v15
	v_cndmask_b32_e32 v66, v7, v164, vcc
	v_cmp_gt_i32_e32 vcc, v68, v134
	v_max3_f32 v67, v6, v65, v66
	ds_read_b128 v[6:9], v14 offset:100
	s_waitcnt lgkmcnt(1)
	v_add_f32_e32 v2, v72, v2
	s_and_b64 vcc, s[60:61], vcc
	v_cndmask_b32_e32 v69, v2, v164, vcc
	v_cmp_ge_i32_e32 vcc, v68, v134
	v_add_f32_e32 v2, v73, v3
	s_and_b64 vcc, s[60:61], vcc
	v_add_f32_e32 v3, v74, v4
	v_add_u32_e32 v4, 18, v15
	v_cndmask_b32_e32 v68, v2, v164, vcc
	v_cmp_gt_i32_e32 vcc, v4, v134
	v_mfma_f32_32x32x16_bf16 v[48:63], v[176:179], v[96:99], v[48:63]
	s_and_b64 vcc, s[60:61], vcc
	v_add_u32_e32 v4, 19, v15
	v_max3_f32 v2, v67, v69, v68
	v_cndmask_b32_e32 v67, v3, v164, vcc
	v_cmp_gt_i32_e32 vcc, v4, v134
	v_add_f32_e32 v3, v75, v5
	s_and_b64 vcc, s[60:61], vcc
	v_cndmask_b32_e32 v70, v3, v164, vcc
	v_add_u32_e32 v3, 24, v15
	v_cmp_gt_i32_e32 vcc, v3, v134
	s_waitcnt lgkmcnt(0)
	v_add_f32_e32 v4, v76, v6
	s_and_b64 vcc, s[60:61], vcc
	v_cndmask_b32_e32 v71, v4, v164, vcc
	v_cmp_ge_i32_e32 vcc, v3, v134
	v_add_f32_e32 v4, v77, v7
	s_and_b64 vcc, s[60:61], vcc
	v_add_u32_e32 v3, 26, v15
	v_mfma_f32_32x32x16_bf16 v[48:63], v[180:183], v[100:103], v[48:63]
	v_max3_f32 v2, v2, v67, v70
	v_cndmask_b32_e32 v72, v4, v164, vcc
	v_cmp_gt_i32_e32 vcc, v3, v134
	v_max3_f32 v6, v2, v71, v72
	v_add_f32_e32 v2, v78, v8
	s_and_b64 vcc, s[60:61], vcc
	v_cndmask_b32_e32 v73, v2, v164, vcc
	v_add_u32_e32 v2, 27, v15
	v_cmp_gt_i32_e32 vcc, v2, v134
	ds_read_b128 v[2:5], v14 offset:132
	v_add_f32_e32 v7, v79, v9
	s_and_b64 vcc, s[60:61], vcc
	v_add_u32_e32 v76, 32, v15
	v_cndmask_b32_e32 v74, v7, v164, vcc
	v_cmp_gt_i32_e32 vcc, v76, v134
	v_max3_f32 v75, v6, v73, v74
	ds_read_b128 v[6:9], v14 offset:164
	s_waitcnt lgkmcnt(1)
	v_add_f32_e32 v2, v48, v2
	s_and_b64 vcc, s[60:61], vcc
	v_cndmask_b32_e32 v48, v2, v164, vcc
	v_cmp_ge_i32_e32 vcc, v76, v134
	v_add_f32_e32 v2, v49, v3
	s_and_b64 vcc, s[60:61], vcc
	v_add_f32_e32 v3, v50, v4
	v_add_u32_e32 v4, 34, v15
	v_cndmask_b32_e32 v49, v2, v164, vcc
	v_cmp_gt_i32_e32 vcc, v4, v134
	s_and_b64 vcc, s[60:61], vcc
	v_add_u32_e32 v4, 35, v15
	v_cndmask_b32_e32 v50, v3, v164, vcc
	v_cmp_gt_i32_e32 vcc, v4, v134
	v_add_f32_e32 v3, v51, v5
	s_and_b64 vcc, s[60:61], vcc
	v_cndmask_b32_e32 v51, v3, v164, vcc
	v_add_u32_e32 v3, 40, v15
	v_cmp_gt_i32_e32 vcc, v3, v134
	s_waitcnt lgkmcnt(0)
	v_add_f32_e32 v4, v52, v6
	s_and_b64 vcc, s[60:61], vcc
	v_cndmask_b32_e32 v52, v4, v164, vcc
	v_cmp_ge_i32_e32 vcc, v3, v134
	v_max3_f32 v2, v75, v48, v49
	v_add_f32_e32 v4, v53, v7
	s_and_b64 vcc, s[60:61], vcc
	v_add_u32_e32 v3, 42, v15
	v_max3_f32 v2, v2, v50, v51
	v_cndmask_b32_e32 v53, v4, v164, vcc
	v_cmp_gt_i32_e32 vcc, v3, v134
	v_max3_f32 v6, v2, v52, v53
	v_add_f32_e32 v2, v54, v8
	s_and_b64 vcc, s[60:61], vcc
	v_cndmask_b32_e32 v54, v2, v164, vcc
	v_add_u32_e32 v2, 43, v15
	v_cmp_gt_i32_e32 vcc, v2, v134
	ds_read_b128 v[2:5], v14 offset:196
	v_add_f32_e32 v7, v55, v9
	s_and_b64 vcc, s[60:61], vcc
	v_add_u32_e32 v76, 48, v15
	v_cndmask_b32_e32 v55, v7, v164, vcc
	v_cmp_gt_i32_e32 vcc, v76, v134
	v_max3_f32 v75, v6, v54, v55
	ds_read_b128 v[6:9], v14 offset:228
	s_waitcnt lgkmcnt(1)
; #define LAS __attribute__((address_space(3)))
; __device__ __forceinline__ float fexp2(float x) { return __builtin_amdgcn_exp2f(x); }
; __device__ __forceinline__ void attn_phase(LAS unsigned char* lds, const int wid, const bf16_t* P, const float* LF, bf16_t* CAT, const float* qgain, const float* kgain) {
;     ...
;                                 float sv = sacc[kb][4 * i4 + jj] + bias[jj];
;                                 if (diag && (kt * 64 + kl + jj > qrow)) sv = -1e30f;
;                                 sacc[kb][4 * i4 + jj] = sv; mloc = fmaxf(mloc, sv);
;                             }
;                         }
;                     mloc = fmaxf(mloc, __shfl_xor(mloc, 32));
;                     const float mnew = fmaxf(mrun, mloc);
;                     const float alpha = fexp2(mrun - mnew); mrun = mnew;
;                     float ps = 0.f;
; #pragma unroll
;                     for (int kb = 0; kb < 2; ++kb)
; #pragma unroll
;                         for (int i = 0; i < 16; ++i) { const float p = fexp2(sacc[kb][i] - mnew); sacc[kb][i] = p; ps += p; }
;                     lsum = lsum * alpha + ps;
; #pragma unroll
;                     for (int i = 0; i < 16; ++i) { O[0][i] *= alpha; O[1][i] *= alpha; }
; #pragma unroll
;                     for (int kb = 0; kb < 2; ++kb)
; #pragma unroll
;                         for (int s2 = 0; s2 < 2; ++s2) {
;                             u32x4 pw; pw.x = cvt_pk_bf16(sacc[kb][8 * s2 + 0], sacc[kb][8 * s2 + 1]); pw.y = cvt_pk_bf16(sacc[kb][8 * s2 + 2], sacc[kb][8 * s2 + 3]);
;                             pw.z = cvt_pk_bf16(sacc[kb][8 * s2 + 4], sacc[kb][8 * s2 + 5]); pw.w = cvt_pk_bf16(sacc[kb][8 * s2 + 6], sacc[kb][8 * s2 + 7]);
;                             const bf16x8 pf = __builtin_bit_cast(bf16x8, pw);
; #pragma unroll
;                             for (int db = 0; db < 2; ++db) {
;                                 const LAS unsigned char* vp = vb_ + (db * 32 + r32) * VPITCH + (kb * 32 + 16 * s2 + 4 * hh) * 2;
;                                 const s16x4 lo = *(const LAS s16x4*)vp, hi = *(const LAS s16x4*)(vp + 16);
;                                 const bf16x8 av = __builtin_shufflevector(lo, hi, 0, 1, 2, 3, 4, 5, 6, 7);
;                                 O[db] = __builtin_amdgcn_mfma_f32_32x32x16_bf16(av, pf, O[db], 0, 0, 0);
;                             }
	v_add_f32_e32 v2, v56, v2
	s_and_b64 vcc, s[60:61], vcc
	v_cndmask_b32_e32 v56, v2, v164, vcc
	v_cmp_ge_i32_e32 vcc, v76, v134
	v_add_f32_e32 v2, v57, v3
	s_and_b64 vcc, s[60:61], vcc
	v_add_f32_e32 v3, v58, v4
	v_add_u32_e32 v4, 50, v15
	v_cndmask_b32_e32 v57, v2, v164, vcc
	v_cmp_gt_i32_e32 vcc, v4, v134
	s_and_b64 vcc, s[60:61], vcc
	v_add_u32_e32 v4, 51, v15
	v_cndmask_b32_e32 v58, v3, v164, vcc
	v_cmp_gt_i32_e32 vcc, v4, v134
	v_add_f32_e32 v3, v59, v5
	s_and_b64 vcc, s[60:61], vcc
	v_cndmask_b32_e32 v59, v3, v164, vcc
	v_add_u32_e32 v3, 56, v15
	v_cmp_gt_i32_e32 vcc, v3, v134
	s_waitcnt lgkmcnt(0)
	v_add_f32_e32 v4, v60, v6
	s_and_b64 vcc, s[60:61], vcc
	v_cndmask_b32_e32 v60, v4, v164, vcc
	v_cmp_ge_i32_e32 vcc, v3, v134
	v_add_f32_e32 v4, v61, v7
	s_and_b64 vcc, s[60:61], vcc
	v_cndmask_b32_e32 v61, v4, v164, vcc
	v_add_u32_e32 v4, 58, v15
	v_cmp_gt_i32_e32 vcc, v4, v134
	v_add_f32_e32 v3, v62, v8
	s_and_b64 vcc, s[60:61], vcc
	v_add_u32_e32 v4, 59, v15
	v_max3_f32 v2, v75, v56, v57
	v_cndmask_b32_e32 v62, v3, v164, vcc
	v_cmp_gt_i32_e32 vcc, v4, v134
	v_max3_f32 v2, v2, v58, v59
	v_add_f32_e32 v3, v63, v9
	s_and_b64 vcc, s[60:61], vcc
	v_max3_f32 v2, v2, v60, v61
	v_cndmask_b32_e32 v15, v3, v164, vcc
	v_max3_f32 v2, v2, v62, v15
	ds_bpermute_b32 v3, v146, v2
	s_waitcnt lgkmcnt(0)
	v_max3_f32 v63, v166, v2, v3
	v_sub_f32_e32 v1, v1, v63
	v_exp_f32_e32 v1, v1
	v_sub_f32_e32 v3, v10, v63
	v_exp_f32_e32 v6, v3
	v_sub_f32_e32 v3, v12, v63
	v_exp_f32_e32 v7, v3
	v_sub_f32_e32 v3, v13, v63
	v_exp_f32_e32 v8, v3
	v_sub_f32_e32 v4, v64, v63
	v_add_f32_e32 v3, 0, v1
	v_exp_f32_e32 v9, v4
	v_sub_f32_e32 v4, v11, v63
	v_add_f32_e32 v3, v6, v3
	v_exp_f32_e32 v10, v4
	v_sub_f32_e32 v4, v65, v63
	v_add_f32_e32 v3, v7, v3
	v_exp_f32_e32 v11, v4
	v_sub_f32_e32 v4, v66, v63
	v_add_f32_e32 v3, v8, v3
	v_exp_f32_e32 v12, v4
	v_sub_f32_e32 v4, v69, v63
	v_add_f32_e32 v3, v9, v3
	v_exp_f32_e32 v64, v4
	v_sub_f32_e32 v4, v68, v63
	v_add_f32_e32 v3, v10, v3
	v_exp_f32_e32 v65, v4
	v_sub_f32_e32 v4, v67, v63
	v_add_f32_e32 v3, v11, v3
	v_exp_f32_e32 v66, v4
	v_sub_f32_e32 v4, v70, v63
	v_add_f32_e32 v3, v12, v3
	v_exp_f32_e32 v67, v4
	v_sub_f32_e32 v4, v71, v63
	v_add_f32_e32 v3, v64, v3
	v_exp_f32_e32 v68, v4
	v_sub_f32_e32 v4, v72, v63
	v_add_f32_e32 v3, v65, v3
	v_exp_f32_e32 v69, v4
	v_sub_f32_e32 v4, v73, v63
	v_add_f32_e32 v3, v66, v3
	v_exp_f32_e32 v70, v4
	v_sub_f32_e32 v4, v74, v63
	v_add_f32_e32 v3, v67, v3
	v_exp_f32_e32 v71, v4
	v_sub_f32_e32 v4, v48, v63
	v_add_f32_e32 v3, v68, v3
	v_exp_f32_e32 v48, v4
	v_sub_f32_e32 v4, v49, v63
	v_add_f32_e32 v3, v69, v3
	v_exp_f32_e32 v49, v4
	v_sub_f32_e32 v4, v50, v63
	v_add_f32_e32 v3, v70, v3
	v_exp_f32_e32 v50, v4
	v_sub_f32_e32 v4, v51, v63
	v_add_f32_e32 v3, v71, v3
	v_exp_f32_e32 v51, v4
	v_sub_f32_e32 v4, v52, v63
	v_add_f32_e32 v3, v48, v3
	v_exp_f32_e32 v52, v4
	v_sub_f32_e32 v4, v53, v63
	v_add_f32_e32 v3, v49, v3
	v_exp_f32_e32 v53, v4
	v_sub_f32_e32 v4, v54, v63
	v_add_f32_e32 v3, v50, v3
	v_exp_f32_e32 v54, v4
	v_add_f32_e32 v3, v51, v3
	v_sub_f32_e32 v2, v166, v63
	v_add_f32_e32 v3, v52, v3
	v_add3_u32 v13, v161, s0, v163
	v_add_f32_e32 v3, v53, v3
	v_exp_f32_e32 v14, v2
	v_sub_f32_e32 v2, v55, v63
	v_add_u32_e32 v73, 0x8800, v13
	v_add_f32_e32 v72, v54, v3
	v_exp_f32_e32 v55, v2
	ds_read2_b64 v[2:5], v73 offset1:2
	v_cvt_pk_bf16_f32 v6, v1, v6
	v_add_u32_e32 v1, 0x9800, v13
	v_cvt_pk_bf16_f32 v7, v7, v8
	v_cvt_pk_bf16_f32 v8, v9, v10
	v_cvt_pk_bf16_f32 v9, v11, v12
	ds_read2_b64 v[10:13], v1 offset0:32 offset1:34
	v_pk_mul_f32 v[46:47], v[46:47], v[14:15] op_sel_hi:[1,0]
	v_pk_mul_f32 v[44:45], v[44:45], v[14:15] op_sel_hi:[1,0]
	v_pk_mul_f32 v[42:43], v[42:43], v[14:15] op_sel_hi:[1,0]
	v_pk_mul_f32 v[40:41], v[40:41], v[14:15] op_sel_hi:[1,0]
	v_pk_mul_f32 v[38:39], v[38:39], v[14:15] op_sel_hi:[1,0]
	v_pk_mul_f32 v[36:37], v[36:37], v[14:15] op_sel_hi:[1,0]
	v_pk_mul_f32 v[34:35], v[34:35], v[14:15] op_sel_hi:[1,0]
	v_pk_mul_f32 v[32:33], v[32:33], v[14:15] op_sel_hi:[1,0]
	v_pk_mul_f32 v[30:31], v[30:31], v[14:15] op_sel_hi:[1,0]
	v_pk_mul_f32 v[28:29], v[28:29], v[14:15] op_sel_hi:[1,0]
	s_waitcnt lgkmcnt(1)
	v_mfma_f32_32x32x16_bf16 v[32:47], v[2:5], v[6:9], v[32:47]
	ds_read2_b64 v[2:5], v73 offset0:4 offset1:6
	v_mul_f32_e64 v26, v26, v14
	v_mul_f32_e64 v27, v27, v14
	v_mul_f32_e64 v24, v24, v14
	v_mul_f32_e64 v25, v25, v14
	v_pk_mul_f32 v[22:23], v[22:23], v[14:15] op_sel_hi:[1,0]
	v_pk_mul_f32 v[20:21], v[20:21], v[14:15] op_sel_hi:[1,0]
	v_pk_mul_f32 v[18:19], v[18:19], v[14:15] op_sel_hi:[1,0]
	v_pk_mul_f32 v[16:17], v[16:17], v[14:15] op_sel_hi:[1,0]
	v_mov_b32_e32 v166, v63
	s_waitcnt lgkmcnt(1)
	v_mfma_f32_32x32x16_bf16 v[16:31], v[10:13], v[6:9], v[16:31]
	v_sub_f32_e32 v6, v56, v63
	v_exp_f32_e32 v56, v6
	ds_read2_b64 v[10:13], v1 offset0:36 offset1:38
	v_cvt_pk_bf16_f32 v6, v64, v65
	v_cvt_pk_bf16_f32 v7, v66, v67
	v_cvt_pk_bf16_f32 v8, v68, v69
	v_cvt_pk_bf16_f32 v9, v70, v71
	s_waitcnt lgkmcnt(1)
	s_nop 0
	v_mfma_f32_32x32x16_bf16 v[32:47], v[2:5], v[6:9], v[32:47]
	v_add_f32_e32 v2, v55, v72
	v_add_f32_e32 v64, v56, v2
	v_sub_f32_e32 v2, v57, v63
	v_exp_f32_e32 v57, v2
	v_sub_f32_e32 v2, v58, v63
	v_exp_f32_e32 v58, v2
	ds_read2_b64 v[2:5], v73 offset0:8 offset1:10
	s_waitcnt lgkmcnt(1)
	v_mfma_f32_32x32x16_bf16 v[16:31], v[10:13], v[6:9], v[16:31]
	ds_read2_b64 v[10:13], v1 offset0:40 offset1:42
	v_sub_f32_e32 v6, v59, v63
	v_exp_f32_e32 v59, v6
	v_cvt_pk_bf16_f32 v6, v48, v49
	v_cvt_pk_bf16_f32 v7, v50, v51
	v_cvt_pk_bf16_f32 v8, v52, v53
	v_cvt_pk_bf16_f32 v9, v54, v55
	s_waitcnt lgkmcnt(1)
	s_nop 0
	v_mfma_f32_32x32x16_bf16 v[32:47], v[2:5], v[6:9], v[32:47]
	v_sub_f32_e32 v2, v60, v63
	v_exp_f32_e32 v48, v2
	v_sub_f32_e32 v2, v61, v63
	v_exp_f32_e32 v49, v2
	v_sub_f32_e32 v2, v62, v63
	v_exp_f32_e32 v50, v2
	ds_read2_b64 v[2:5], v73 offset0:12 offset1:14
	s_waitcnt lgkmcnt(1)
	v_mfma_f32_32x32x16_bf16 v[16:31], v[10:13], v[6:9], v[16:31]
	ds_read2_b64 v[10:13], v1 offset0:44 offset1:46
	v_sub_f32_e32 v6, v15, v63
	v_exp_f32_e32 v15, v6
	v_cvt_pk_bf16_f32 v6, v56, v57
	v_cvt_pk_bf16_f32 v7, v58, v59
	v_cvt_pk_bf16_f32 v8, v48, v49
	v_cvt_pk_bf16_f32 v9, v50, v15
	v_add_f32_e32 v1, v57, v64
	v_add_f32_e32 v1, v58, v1
	s_waitcnt lgkmcnt(1)
	v_mfma_f32_32x32x16_bf16 v[32:47], v[2:5], v[6:9], v[32:47]
	v_add_f32_e32 v1, v59, v1
	v_add_f32_e32 v1, v48, v1
	v_add_f32_e32 v1, v49, v1
	v_add_f32_e32 v1, v50, v1
	v_add_f32_e32 v1, v15, v1
	v_fmac_f32_e32 v1, v135, v14
	v_mov_b32_e32 v135, v1
	s_waitcnt lgkmcnt(0)
	v_mfma_f32_32x32x16_bf16 v[16:31], v[10:13], v[6:9], v[16:31]

; #define LAS __attribute__((address_space(3)))
; __device__ __forceinline__ void attn_phase(LAS unsigned char* lds, const int wid, const bf16_t* P, const float* LF, bf16_t* CAT, const float* qgain, const float* kgain) {
;     ...
;                 if (kt * 64 <= q0 + 31 && !done_w) {
;                     const LAS unsigned char* kb_ = KB + cb * 64 * KPITCH;
;                     const LAS unsigned char* vb_ = VB + cb * 64 * VPITCH;
;                     f32x16 sacc[2];
; #pragma unroll
;                     for (int kb = 0; kb < 2; ++kb) {
; #pragma unroll
;                         for (int i = 0; i < 16; ++i) sacc[kb][i] = 0.f;
; #pragma unroll
;                         for (int ds = 0; ds < 4; ++ds) {
;                             const bf16x8 a = *(const LAS bf16x8*)(kb_ + (kb * 32 + r32) * KPITCH + (16 * ds + 8 * hh) * 2);
;                             sacc[kb] = __builtin_amdgcn_mfma_f32_32x32x16_bf16(a, qf[ds], sacc[kb], 0, 0, 0);
;                         }
;                     }
;                     const bool diag = (kt * 64 + 63 > q0);
;                     float mloc = -1e30f;
; #pragma unroll
;                     for (int kb = 0; kb < 2; ++kb)
; #pragma unroll
;                         for (int i4 = 0; i4 < 4; ++i4) {
;                             const int kl = kb * 32 + 8 * i4 + 4 * hh;
;                             const f32x4 bias = *(const LAS f32x4*)(CB + kt * 64 + kl);
; #pragma unroll
;                             for (int jj = 0; jj < 4; ++jj) {
;                                 float sv = sacc[kb][4 * i4 + jj] + bias[jj];
;                                 if (diag && (kt * 64 + kl + jj > qrow)) sv = -1e30f;
;                                 sacc[kb][4 * i4 + jj] = sv; mloc = fmaxf(mloc, sv);
;                             }
;                         }
;                     mloc = fmaxf(mloc, __shfl_xor(mloc, 32));
.Lattn_nodiag_b:
	s_mul_i32 s0, s80, 0x2400
	v_add3_u32 v1, v160, s0, v162
	ds_read_b128 v[2:5], v1 offset:16384
	ds_read_b128 v[6:9], v1 offset:16416
	v_add_u32_e32 v14, s78, v159
	s_add_i32 s0, s77, 63
	v_add_u32_e32 v15, s77, v112
	s_waitcnt lgkmcnt(1)
	v_mfma_f32_32x32x16_bf16 v[64:79], v[2:5], v[88:91], 0
	ds_read_b128 v[2:5], v1 offset:16448
	s_cmp_gt_i32 s0, s74
	s_cselect_b64 s[60:61], -1, 0
	s_mul_i32 s0, s80, 0x2200
	s_waitcnt lgkmcnt(1)
	v_mfma_f32_32x32x16_bf16 v[64:79], v[6:9], v[92:95], v[64:79]
	ds_read_b128 v[6:9], v1 offset:16480
	ds_read_b128 v[10:13], v1 offset:20992
	s_waitcnt lgkmcnt(2)
	v_mfma_f32_32x32x16_bf16 v[64:79], v[2:5], v[96:99], v[64:79]
	ds_read_b128 v[2:5], v14 offset:4
	ds_read_b128 v[168:171], v14 offset:36
	ds_read_b128 v[172:175], v1 offset:21024
	ds_read_b128 v[176:179], v1 offset:21056
	ds_read_b128 v[180:183], v1 offset:21088
	s_waitcnt lgkmcnt(6)
	v_mfma_f32_32x32x16_bf16 v[64:79], v[6:9], v[100:103], v[64:79]
	s_waitcnt lgkmcnt(5)
	v_mfma_f32_32x32x16_bf16 v[48:63], v[10:13], v[88:91], 0
	s_waitcnt lgkmcnt(4)
	s_nop 8
	v_add_f32_e32 v1, v64, v2
	v_add_f32_e32 v10, v65, v3
	v_add_f32_e32 v12, v66, v4
	v_add_f32_e32 v13, v67, v5
	s_waitcnt lgkmcnt(3)
	v_add_f32_e32 v64, v68, v168
	v_add_f32_e32 v11, v69, v169
	v_max3_f32 v2, v1, s67, v10
	v_max3_f32 v2, v2, v12, v13
	v_max3_f32 v6, v2, v64, v11
	v_add_f32_e32 v65, v70, v170
	ds_read_b128 v[2:5], v14 offset:68
	s_waitcnt lgkmcnt(3)
	v_mfma_f32_32x32x16_bf16 v[48:63], v[172:175], v[92:95], v[48:63]
	v_add_f32_e32 v66, v71, v171
	v_max3_f32 v67, v6, v65, v66
	ds_read_b128 v[6:9], v14 offset:100
	s_waitcnt lgkmcnt(1)
	v_add_f32_e32 v69, v72, v2
	v_add_f32_e32 v68, v73, v3
	v_add_f32_e32 v3, v74, v4
	v_mfma_f32_32x32x16_bf16 v[48:63], v[176:179], v[96:99], v[48:63]
	v_max3_f32 v2, v67, v69, v68
	v_mov_b32_e32 v67, v3
	v_add_f32_e32 v70, v75, v5
	s_waitcnt lgkmcnt(0)
	v_add_f32_e32 v71, v76, v6
	v_add_f32_e32 v72, v77, v7
	v_mfma_f32_32x32x16_bf16 v[48:63], v[180:183], v[100:103], v[48:63]
	v_max3_f32 v2, v2, v67, v70
	v_max3_f32 v6, v2, v71, v72
	v_add_f32_e32 v73, v78, v8
	ds_read_b128 v[2:5], v14 offset:132
	v_add_f32_e32 v74, v79, v9
	v_max3_f32 v75, v6, v73, v74
	ds_read_b128 v[6:9], v14 offset:164
	s_waitcnt lgkmcnt(1)
	s_nop 3
	v_add_f32_e32 v2, v48, v2
	v_mov_b32_e32 v48, v2
	v_add_f32_e32 v2, v49, v3
	v_add_f32_e32 v3, v50, v4
	v_mov_b32_e32 v49, v2
	v_mov_b32_e32 v50, v3
	v_add_f32_e32 v3, v51, v5
	v_mov_b32_e32 v51, v3
	s_waitcnt lgkmcnt(0)
	v_add_f32_e32 v4, v52, v6
	v_mov_b32_e32 v52, v4
	v_max3_f32 v2, v75, v48, v49
	v_add_f32_e32 v4, v53, v7
	v_max3_f32 v2, v2, v50, v51
	v_mov_b32_e32 v53, v4
	v_max3_f32 v6, v2, v52, v53
	v_add_f32_e32 v2, v54, v8
	v_mov_b32_e32 v54, v2
	ds_read_b128 v[2:5], v14 offset:196
	v_add_f32_e32 v7, v55, v9
	v_add_u32_e32 v76, 48, v15
	v_mov_b32_e32 v55, v7
	v_max3_f32 v75, v6, v54, v55
	ds_read_b128 v[6:9], v14 offset:228
	s_waitcnt lgkmcnt(1)
	v_add_f32_e32 v2, v56, v2
	v_mov_b32_e32 v56, v2
	v_add_f32_e32 v2, v57, v3
	v_add_f32_e32 v3, v58, v4
	v_mov_b32_e32 v57, v2
	v_mov_b32_e32 v58, v3
	v_add_f32_e32 v3, v59, v5
	v_mov_b32_e32 v59, v3
	s_waitcnt lgkmcnt(0)
	v_add_f32_e32 v4, v60, v6
	v_mov_b32_e32 v60, v4
	v_add_f32_e32 v4, v61, v7
	v_mov_b32_e32 v61, v4
	v_add_f32_e32 v3, v62, v8
	v_max3_f32 v2, v75, v56, v57
	v_mov_b32_e32 v62, v3
	v_max3_f32 v2, v2, v58, v59
	v_add_f32_e32 v15, v63, v9
	v_max3_f32 v2, v2, v60, v61
	v_max3_f32 v2, v2, v62, v15
	ds_bpermute_b32 v3, v146, v2
	s_waitcnt lgkmcnt(0)
; #define LAS __attribute__((address_space(3)))
; __device__ __forceinline__ unsigned cvt_pk_bf16(float lo, float hi) { const f32x2 v = {lo, hi}; return __builtin_bit_cast(unsigned, __builtin_convertvector(v, b16x2_t)); }
; __device__ __forceinline__ float fexp2(float x) { return __builtin_amdgcn_exp2f(x); }
; __device__ __forceinline__ void attn_phase(LAS unsigned char* lds, const int wid, const bf16_t* P, const float* LF, bf16_t* CAT, const float* qgain, const float* kgain) {
;     ...
;                     mloc = fmaxf(mloc, __shfl_xor(mloc, 32));
;                     const float mnew = fmaxf(mrun, mloc);
;                     const float alpha = fexp2(mrun - mnew); mrun = mnew;
;                     float ps = 0.f;
; #pragma unroll
;                     for (int kb = 0; kb < 2; ++kb)
; #pragma unroll
;                         for (int i = 0; i < 16; ++i) { const float p = fexp2(sacc[kb][i] - mnew); sacc[kb][i] = p; ps += p; }
;                     lsum = lsum * alpha + ps;
; #pragma unroll
;                     for (int i = 0; i < 16; ++i) { O[0][i] *= alpha; O[1][i] *= alpha; }
; #pragma unroll
;                     for (int kb = 0; kb < 2; ++kb)
; #pragma unroll
;                         for (int s2 = 0; s2 < 2; ++s2) {
;                             u32x4 pw; pw.x = cvt_pk_bf16(sacc[kb][8 * s2 + 0], sacc[kb][8 * s2 + 1]); pw.y = cvt_pk_bf16(sacc[kb][8 * s2 + 2], sacc[kb][8 * s2 + 3]);
;                             pw.z = cvt_pk_bf16(sacc[kb][8 * s2 + 4], sacc[kb][8 * s2 + 5]); pw.w = cvt_pk_bf16(sacc[kb][8 * s2 + 6], sacc[kb][8 * s2 + 7]);
;                             const bf16x8 pf = __builtin_bit_cast(bf16x8, pw);
; #pragma unroll
;                             for (int db = 0; db < 2; ++db) {
;                                 const LAS unsigned char* vp = vb_ + (db * 32 + r32) * VPITCH + (kb * 32 + 16 * s2 + 4 * hh) * 2;
;                                 const s16x4 lo = *(const LAS s16x4*)vp, hi = *(const LAS s16x4*)(vp + 16);
;                                 const bf16x8 av = __builtin_shufflevector(lo, hi, 0, 1, 2, 3, 4, 5, 6, 7);
;                                 O[db] = __builtin_amdgcn_mfma_f32_32x32x16_bf16(av, pf, O[db], 0, 0, 0);
;                             }
;                         }
;                 }
	v_max3_f32 v63, v166, v2, v3
	v_sub_f32_e32 v1, v1, v63
	v_exp_f32_e32 v1, v1
	v_sub_f32_e32 v3, v10, v63
	v_exp_f32_e32 v6, v3
	v_sub_f32_e32 v3, v12, v63
	v_exp_f32_e32 v7, v3
	v_sub_f32_e32 v3, v13, v63
	v_exp_f32_e32 v8, v3
	v_sub_f32_e32 v4, v64, v63
	v_add_f32_e32 v3, 0, v1
	v_exp_f32_e32 v9, v4
	v_sub_f32_e32 v4, v11, v63
	v_add_f32_e32 v3, v6, v3
	v_exp_f32_e32 v10, v4
	v_sub_f32_e32 v4, v65, v63
	v_add_f32_e32 v3, v7, v3
	v_exp_f32_e32 v11, v4
	v_sub_f32_e32 v4, v66, v63
	v_add_f32_e32 v3, v8, v3
	v_exp_f32_e32 v12, v4
	v_sub_f32_e32 v4, v69, v63
	v_add_f32_e32 v3, v9, v3
	v_exp_f32_e32 v64, v4
	v_sub_f32_e32 v4, v68, v63
	v_add_f32_e32 v3, v10, v3
	v_exp_f32_e32 v65, v4
	v_sub_f32_e32 v4, v67, v63
	v_add_f32_e32 v3, v11, v3
	v_exp_f32_e32 v66, v4
	v_sub_f32_e32 v4, v70, v63
	v_add_f32_e32 v3, v12, v3
	v_exp_f32_e32 v67, v4
	v_sub_f32_e32 v4, v71, v63
	v_add_f32_e32 v3, v64, v3
	v_exp_f32_e32 v68, v4
	v_sub_f32_e32 v4, v72, v63
	v_add_f32_e32 v3, v65, v3
	v_exp_f32_e32 v69, v4
	v_sub_f32_e32 v4, v73, v63
	v_add_f32_e32 v3, v66, v3
	v_exp_f32_e32 v70, v4
	v_sub_f32_e32 v4, v74, v63
	v_add_f32_e32 v3, v67, v3
	v_exp_f32_e32 v71, v4
	v_sub_f32_e32 v4, v48, v63
	v_add_f32_e32 v3, v68, v3
	v_exp_f32_e32 v48, v4
	v_sub_f32_e32 v4, v49, v63
	v_add_f32_e32 v3, v69, v3
	v_exp_f32_e32 v49, v4
	v_sub_f32_e32 v4, v50, v63
	v_add_f32_e32 v3, v70, v3
	v_exp_f32_e32 v50, v4
	v_sub_f32_e32 v4, v51, v63
	v_add_f32_e32 v3, v71, v3
	v_exp_f32_e32 v51, v4
	v_sub_f32_e32 v4, v52, v63
	v_add_f32_e32 v3, v48, v3
	v_exp_f32_e32 v52, v4
	v_sub_f32_e32 v4, v53, v63
	v_add_f32_e32 v3, v49, v3
	v_exp_f32_e32 v53, v4
	v_sub_f32_e32 v4, v54, v63
	v_add_f32_e32 v3, v50, v3
	v_exp_f32_e32 v54, v4
	v_add_f32_e32 v3, v51, v3
	v_sub_f32_e32 v2, v166, v63
	v_add_f32_e32 v3, v52, v3
	v_add3_u32 v13, v161, s0, v163
	v_add_f32_e32 v3, v53, v3
	v_exp_f32_e32 v14, v2
	v_sub_f32_e32 v2, v55, v63
	v_add_u32_e32 v73, 0x8800, v13
	v_add_f32_e32 v72, v54, v3
	v_exp_f32_e32 v55, v2
	ds_read2_b64 v[2:5], v73 offset1:2
	v_cvt_pk_bf16_f32 v6, v1, v6
	v_add_u32_e32 v1, 0x9800, v13
	v_cvt_pk_bf16_f32 v7, v7, v8
	v_cvt_pk_bf16_f32 v8, v9, v10
	v_cvt_pk_bf16_f32 v9, v11, v12
	ds_read2_b64 v[10:13], v1 offset0:32 offset1:34
	v_pk_mul_f32 v[46:47], v[46:47], v[14:15] op_sel_hi:[1,0]
	v_pk_mul_f32 v[44:45], v[44:45], v[14:15] op_sel_hi:[1,0]
	v_pk_mul_f32 v[42:43], v[42:43], v[14:15] op_sel_hi:[1,0]
	v_pk_mul_f32 v[40:41], v[40:41], v[14:15] op_sel_hi:[1,0]
	v_pk_mul_f32 v[38:39], v[38:39], v[14:15] op_sel_hi:[1,0]
	v_pk_mul_f32 v[36:37], v[36:37], v[14:15] op_sel_hi:[1,0]
	v_pk_mul_f32 v[34:35], v[34:35], v[14:15] op_sel_hi:[1,0]
	v_pk_mul_f32 v[32:33], v[32:33], v[14:15] op_sel_hi:[1,0]
	v_pk_mul_f32 v[30:31], v[30:31], v[14:15] op_sel_hi:[1,0]
	v_pk_mul_f32 v[28:29], v[28:29], v[14:15] op_sel_hi:[1,0]
	s_waitcnt lgkmcnt(1)
	v_mfma_f32_32x32x16_bf16 v[32:47], v[2:5], v[6:9], v[32:47]
	ds_read2_b64 v[2:5], v73 offset0:4 offset1:6
	v_mul_f32_e64 v26, v26, v14
	v_mul_f32_e64 v27, v27, v14
	v_mul_f32_e64 v24, v24, v14
	v_mul_f32_e64 v25, v25, v14
	v_pk_mul_f32 v[22:23], v[22:23], v[14:15] op_sel_hi:[1,0]
	v_pk_mul_f32 v[20:21], v[20:21], v[14:15] op_sel_hi:[1,0]
	v_pk_mul_f32 v[18:19], v[18:19], v[14:15] op_sel_hi:[1,0]
	v_pk_mul_f32 v[16:17], v[16:17], v[14:15] op_sel_hi:[1,0]
	v_mov_b32_e32 v166, v63
	s_waitcnt lgkmcnt(1)
	v_mfma_f32_32x32x16_bf16 v[16:31], v[10:13], v[6:9], v[16:31]
	v_sub_f32_e32 v6, v56, v63
	v_exp_f32_e32 v56, v6
	ds_read2_b64 v[10:13], v1 offset0:36 offset1:38
	v_cvt_pk_bf16_f32 v6, v64, v65
	v_cvt_pk_bf16_f32 v7, v66, v67
	v_cvt_pk_bf16_f32 v8, v68, v69
	v_cvt_pk_bf16_f32 v9, v70, v71
	s_waitcnt lgkmcnt(1)
	s_nop 0
	v_mfma_f32_32x32x16_bf16 v[32:47], v[2:5], v[6:9], v[32:47]
	v_add_f32_e32 v2, v55, v72
	v_add_f32_e32 v64, v56, v2
	v_sub_f32_e32 v2, v57, v63
	v_exp_f32_e32 v57, v2
	v_sub_f32_e32 v2, v58, v63
	v_exp_f32_e32 v58, v2
	ds_read2_b64 v[2:5], v73 offset0:8 offset1:10
	s_waitcnt lgkmcnt(1)
	v_mfma_f32_32x32x16_bf16 v[16:31], v[10:13], v[6:9], v[16:31]
	ds_read2_b64 v[10:13], v1 offset0:40 offset1:42
	v_sub_f32_e32 v6, v59, v63
	v_exp_f32_e32 v59, v6
	v_cvt_pk_bf16_f32 v6, v48, v49
	v_cvt_pk_bf16_f32 v7, v50, v51
	v_cvt_pk_bf16_f32 v8, v52, v53
	v_cvt_pk_bf16_f32 v9, v54, v55
	s_waitcnt lgkmcnt(1)
	s_nop 0
	v_mfma_f32_32x32x16_bf16 v[32:47], v[2:5], v[6:9], v[32:47]
	v_sub_f32_e32 v2, v60, v63
	v_exp_f32_e32 v48, v2
	v_sub_f32_e32 v2, v61, v63
	v_exp_f32_e32 v49, v2
	v_sub_f32_e32 v2, v62, v63
	v_exp_f32_e32 v50, v2
	ds_read2_b64 v[2:5], v73 offset0:12 offset1:14
	s_waitcnt lgkmcnt(1)
	v_mfma_f32_32x32x16_bf16 v[16:31], v[10:13], v[6:9], v[16:31]
	ds_read2_b64 v[10:13], v1 offset0:44 offset1:46
	v_sub_f32_e32 v6, v15, v63
	v_exp_f32_e32 v15, v6
	v_cvt_pk_bf16_f32 v6, v56, v57
	v_cvt_pk_bf16_f32 v7, v58, v59
	v_cvt_pk_bf16_f32 v8, v48, v49
	v_cvt_pk_bf16_f32 v9, v50, v15
	v_add_f32_e32 v1, v57, v64
	v_add_f32_e32 v1, v58, v1
	s_waitcnt lgkmcnt(1)
	v_mfma_f32_32x32x16_bf16 v[32:47], v[2:5], v[6:9], v[32:47]
	v_add_f32_e32 v1, v59, v1
	v_add_f32_e32 v1, v48, v1
	v_add_f32_e32 v1, v49, v1
	v_add_f32_e32 v1, v50, v1
	v_add_f32_e32 v1, v15, v1
	v_fmac_f32_e32 v1, v135, v14
	v_mov_b32_e32 v135, v1
	s_waitcnt lgkmcnt(0)
	v_mfma_f32_32x32x16_bf16 v[16:31], v[10:13], v[6:9], v[16:31]
	s_branch .LBB0_1902
